# dilated attention: bias-table load issued with the tile loads (one round trip less per unit), on top of lean masked path + MLA body + phase-0 rotation
# baseline (speedup 1.0000x reference)
.LBB0_699:
	s_and_b32 s2, s10, 0x3fffffc0
	s_lshl_b32 s2, s2, 2
	s_add_i32 s17, s2, 0
	s_mul_hi_i32 s2, s8, 0x2aaaaaab
	s_lshr_b32 s6, s2, 31
	s_ashr_i32 s2, s2, 6
	s_add_i32 s17, s17, 0x1c800
	s_and_b32 s3, s38, 31
	s_bfe_u32 s19, s8, 0x20005
	s_add_i32 s2, s2, s6
	s_cmp_eq_u32 s18, 1
	s_cselect_b32 s6, 2, 4
	s_cmp_lg_u32 s18, 0
	s_cselect_b32 s16, s6, 0
	s_lshr_b32 s6, 32, s16
	s_sub_i32 s7, 5, s16
	s_add_i32 s6, s6, -1
	s_lshr_b32 s8, s3, s7
	s_and_b32 s3, s6, s3
	s_lshl_b32 s21, s3, 8
	s_ashr_i32 s3, s2, 31
	s_lshl_b64 s[6:7], s[2:3], 13
	s_lshl_b32 s2, s18, 8
	s_ashr_i32 s3, s2, 31
	s_or_b32 s6, s6, s8
	s_lshl_b64 s[8:9], s[2:3], 1
	s_sub_i32 s2, s21, 64
	v_ashrrev_i32_e32 v1, 3, v0
	s_lshr_b32 s20, 0x2000, s16
	v_add_u32_e32 v2, s2, v1
	v_max_i32_e32 v2, 0, v2
	s_add_i32 s2, s20, -1
	v_min_u32_e32 v2, s2, v2
	v_mov_b32_e32 v3, v233
	v_add_u32_e32 v42, s21, v1
	v_lshlrev_b64 v[2:3], s16, v[2:3]
	v_max_i32_e32 v10, 0, v42
	v_lshl_add_u64 v[2:3], v[2:3], 0, s[6:7]
	v_min_u32_e32 v10, s2, v10
	v_mov_b32_e32 v11, v233
	v_add_u32_e32 v18, 64, v42
	v_readlane_b32 s48, v254, 32
	v_lshlrev_b64 v[2:3], 13, v[2:3]
	v_lshlrev_b64 v[10:11], s16, v[10:11]
	v_max_i32_e32 v18, 0, v18
	v_readlane_b32 s49, v254, 33
	v_lshl_add_u64 v[2:3], s[74:75], 0, v[2:3]
	v_lshl_add_u64 v[10:11], v[10:11], 0, s[6:7]
	v_min_u32_e32 v18, s2, v18
	v_mov_b32_e32 v19, v233
	v_add_u32_e32 v26, 0x80, v42
	s_mov_b32 s13, s49
	s_lshl_b32 s12, s19, 7
	v_lshl_add_u64 v[2:3], v[2:3], 0, s[8:9]
	v_lshlrev_b32_e32 v4, 4, v0
	v_lshlrev_b64 v[10:11], 13, v[10:11]
	v_lshlrev_b64 v[18:19], s16, v[18:19]
	v_max_i32_e32 v26, 0, v26
	v_lshl_add_u64 v[2:3], v[2:3], 0, s[12:13]
	s_waitcnt vmcnt(0)
	v_cmp_gt_i32_e64 s[30:31], s37, v0
	s_and_saveexec_b64 s[34:35], s[30:31]
	s_bfe_u32 s28, s15, 0x20005
	s_mulk_i32 s28, 0x84
	s_mul_i32 s29, s18, 0x210
	s_add_i32 s29, s29, s28
	v_add_u32_e32 v200, s29, v0
	v_ashrrev_i32_e32 v201, 31, v200
	v_lshl_add_u64 v[200:201], v[200:201], 2, s[4:5]
	flat_load_dword v202, v[200:201]
	s_or_b64 exec, exec, s[34:35]
	v_and_b32_e32 v50, 0x70, v4
	v_mov_b32_e32 v51, v233
	v_lshl_add_u64 v[10:11], s[74:75], 0, v[10:11]
	v_lshl_add_u64 v[18:19], v[18:19], 0, s[6:7]
	v_min_u32_e32 v26, s2, v26
	v_mov_b32_e32 v27, v233
	v_add_u32_e32 v34, 0xc0, v42
	v_lshl_add_u64 v[2:3], v[2:3], 0, v[50:51]
	v_lshl_add_u64 v[10:11], v[10:11], 0, s[8:9]
	v_lshlrev_b64 v[18:19], 13, v[18:19]
	v_lshlrev_b64 v[26:27], s16, v[26:27]
	v_max_i32_e32 v34, 0, v34
	v_add_co_u32_e32 v6, vcc, s36, v2
	v_lshl_add_u64 v[10:11], v[10:11], 0, s[12:13]
	v_lshl_add_u64 v[18:19], s[74:75], 0, v[18:19]
	v_lshl_add_u64 v[26:27], v[26:27], 0, s[6:7]
	v_min_u32_e32 v34, s2, v34
	v_mov_b32_e32 v35, v233
	v_add_u32_e32 v42, 0x100, v42
	v_addc_co_u32_e32 v7, vcc, 0, v3, vcc
	v_lshl_add_u64 v[10:11], v[10:11], 0, v[50:51]
	v_lshl_add_u64 v[18:19], v[18:19], 0, s[8:9]
	v_lshlrev_b64 v[26:27], 13, v[26:27]
	v_lshlrev_b64 v[34:35], s16, v[34:35]
	v_max_i32_e32 v42, 0, v42
	v_add_co_u32_e32 v14, vcc, s36, v10
	v_lshl_add_u64 v[18:19], v[18:19], 0, s[12:13]
	v_lshl_add_u64 v[26:27], s[74:75], 0, v[26:27]
	v_lshl_add_u64 v[34:35], v[34:35], 0, s[6:7]
	v_min_u32_e32 v42, s2, v42
	v_mov_b32_e32 v43, v233
	v_addc_co_u32_e32 v15, vcc, 0, v11, vcc
	v_lshl_add_u64 v[18:19], v[18:19], 0, v[50:51]
	v_lshl_add_u64 v[26:27], v[26:27], 0, s[8:9]
	v_lshlrev_b64 v[34:35], 13, v[34:35]
	v_lshlrev_b64 v[42:43], s16, v[42:43]
	v_add_co_u32_e32 v22, vcc, s36, v18
	v_lshl_add_u64 v[26:27], v[26:27], 0, s[12:13]
	v_lshl_add_u64 v[34:35], s[74:75], 0, v[34:35]
	v_lshl_add_u64 v[42:43], v[42:43], 0, s[6:7]
	s_ashr_i32 s10, s10, 1
	v_addc_co_u32_e32 v23, vcc, 0, v19, vcc
	v_lshl_add_u64 v[26:27], v[26:27], 0, v[50:51]
	v_lshl_add_u64 v[34:35], v[34:35], 0, s[8:9]
	v_lshlrev_b64 v[42:43], 13, v[42:43]
	s_and_b32 s11, s10, 0xffffffe0
	v_add_co_u32_e32 v30, vcc, s36, v26
	v_lshl_add_u64 v[34:35], v[34:35], 0, s[12:13]
	v_lshl_add_u64 v[42:43], s[74:75], 0, v[42:43]
	v_and_b32_e32 v82, 31, v0
	s_add_i32 s22, s11, s21
	v_addc_co_u32_e32 v31, vcc, 0, v27, vcc
	v_lshl_add_u64 v[34:35], v[34:35], 0, v[50:51]
	v_lshl_add_u64 v[42:43], v[42:43], 0, s[8:9]
	v_or_b32_e32 v52, s22, v82
	flat_load_dwordx4 v[2:5], v[6:7] offset:832
	s_nop 0
	flat_load_dwordx4 v[6:9], v[6:7] offset:2368
	s_nop 0
	flat_load_dwordx4 v[10:13], v[14:15] offset:832
	s_nop 0
	flat_load_dwordx4 v[14:17], v[14:15] offset:2368
	v_add_co_u32_e32 v38, vcc, s36, v34
	v_lshl_add_u64 v[42:43], v[42:43], 0, s[12:13]
	v_ashrrev_i32_e32 v53, 31, v52
	flat_load_dwordx4 v[18:21], v[22:23] offset:832
	s_nop 0
	flat_load_dwordx4 v[22:25], v[22:23] offset:2368
	v_addc_co_u32_e32 v39, vcc, 0, v35, vcc
	v_lshl_add_u64 v[42:43], v[42:43], 0, v[50:51]
	v_lshlrev_b64 v[52:53], s16, v[52:53]
	flat_load_dwordx4 v[26:29], v[30:31] offset:832
	s_nop 0
	flat_load_dwordx4 v[30:33], v[30:31] offset:2368
	v_add_co_u32_e32 v46, vcc, s36, v42
	v_lshl_add_u64 v[80:81], v[52:53], 0, s[6:7]
	flat_load_dwordx4 v[34:37], v[38:39] offset:832
	s_nop 0
	flat_load_dwordx4 v[38:41], v[38:39] offset:2368
	v_addc_co_u32_e32 v47, vcc, 0, v43, vcc
	v_lshlrev_b64 v[52:53], 13, v[80:81]
	flat_load_dwordx4 v[42:45], v[46:47] offset:832
	s_nop 0
	flat_load_dwordx4 v[46:49], v[46:47] offset:2368
	v_lshl_add_u64 v[52:53], s[74:75], 0, v[52:53]
	v_bfe_u32 v51, v0, 5, 1
	v_lshl_add_u64 v[52:53], v[52:53], 0, s[8:9]
	v_lshl_add_u64 v[52:53], v[52:53], 0, s[12:13]
	v_lshlrev_b32_e32 v232, 4, v51
	v_lshl_add_u64 v[52:53], v[52:53], 0, v[232:233]
	flat_load_dwordx4 v[64:67], v[52:53] offset:3392
	flat_load_dwordx4 v[68:71], v[52:53] offset:3424
	flat_load_dwordx4 v[72:75], v[52:53] offset:3456
	flat_load_dwordx4 v[76:79], v[52:53] offset:3488
	s_movk_i32 s12, 0x90
	v_mul_lo_u32 v1, v1, s12
	v_add3_u32 v52, 0, v1, v50
	s_add_i32 s3, 0, 0x12000
	s_waitcnt vmcnt(0) lgkmcnt(0)
	s_and_saveexec_b64 s[34:35], s[30:31]
	v_lshl_add_u32 v203, v0, 2, v251
	ds_write_b32 v203, v202
	s_or_b64 exec, exec, s[34:35]
	ds_write_b128 v52, v[2:5]
	ds_write_b128 v52, v[6:9] offset:55296
	ds_write_b128 v52, v[10:13] offset:9216
	ds_write_b128 v52, v[14:17] offset:64512
	ds_write_b128 v52, v[18:21] offset:18432
	v_add3_u32 v2, s3, v1, v50
	ds_write_b128 v2, v[22:25]
	ds_write_b128 v52, v[26:29] offset:27648
	v_add3_u32 v2, s89, v1, v50
	v_readlane_b32 s3, v254, 10
	ds_write_b128 v2, v[30:33]
	ds_write_b128 v52, v[34:37] offset:36864
	v_add3_u32 v2, s3, v1, v50
	ds_write_b128 v2, v[38:41]
	ds_write_b128 v52, v[42:45] offset:46080
	v_readlane_b32 s3, v254, 11
	v_lshlrev_b32_e32 v2, 2, v82
	s_lshl_b32 s10, s10, 2
	v_add3_u32 v1, s3, v1, v50
	v_lshlrev_b32_e32 v83, 2, v51
	v_add_u32_e32 v84, s17, v2
	v_sub_u32_e32 v2, v232, v2
	s_and_b32 s10, s10, 0xffffff80
	ds_write_b128 v1, v[46:49]
	v_lshrrev_b32_e32 v1, 2, v0
	v_subrev_u32_e32 v86, s10, v2
	v_sub_u32_e32 v2, v83, v82
	v_and_or_b32 v1, v1, 3, v83
	v_subrev_u32_e32 v87, s11, v2
	v_lshlrev_b32_e32 v2, 1, v0
	v_and_b32_e32 v0, 3, v0
	s_max_i32 s3, s22, 64
	v_mul_u32_u24_e32 v1, 0x90, v1
	v_and_b32_e32 v2, 32, v2
	v_lshlrev_b32_e32 v0, 3, v0
	v_mov_b32_e32 v14, v233
	v_mov_b32_e32 v15, v233
	s_sub_i32 s25, s3, 64
	s_add_i32 s3, s22, 0x5f
	v_add3_u32 v90, v1, v2, v0
	v_mov_b32_e32 v0, v233
	v_mov_b32_e32 v1, v233
	v_mov_b32_e32 v2, v233
	v_mov_b32_e32 v3, v233
	v_mov_b32_e32 v4, v233
	v_mov_b32_e32 v5, v233
	v_mov_b32_e32 v6, v233
	v_mov_b32_e32 v7, v233
	v_mov_b32_e32 v8, v233
	v_mov_b32_e32 v9, v233
	v_mov_b32_e32 v10, v233
	v_mov_b32_e32 v11, v233
	v_mov_b32_e32 v12, v233
	v_mov_b32_e32 v13, v233
	v_mov_b64_e32 v[30:31], v[14:15]
	s_mov_b32 s41, s49
	s_mov_b32 s24, 0
	s_lshl_b32 s23, s19, 6
	s_min_i32 s26, s3, s2
	v_cmp_eq_u32_e64 s[2:3], 0, v51
	s_sub_i32 s27, 0, s11
	v_lshl_add_u32 v88, v87, 2, v251
	v_or_b32_e32 v89, s21, v83
	v_mad_u32_u24 v91, v82, s12, v232
	v_mov_b32_e32 v85, 0
	v_mov_b32_e32 v92, 0xf149f2ca
	v_mov_b64_e32 v[28:29], v[12:13]
	v_mov_b64_e32 v[26:27], v[10:11]
	v_mov_b64_e32 v[24:25], v[8:9]
	v_mov_b64_e32 v[22:23], v[6:7]
	v_mov_b64_e32 v[20:21], v[4:5]
	v_mov_b64_e32 v[18:19], v[2:3]
	v_mov_b64_e32 v[16:17], v[0:1]
	v_readlane_b32 s50, v254, 34
	v_readlane_b32 s51, v254, 35
	v_readlane_b32 s52, v254, 36
	v_readlane_b32 s53, v254, 37
	v_readlane_b32 s54, v254, 38
	v_readlane_b32 s55, v254, 39
	v_readlane_b32 s56, v254, 40
	v_readlane_b32 s57, v254, 41
	v_readlane_b32 s58, v254, 42
	v_readlane_b32 s59, v254, 43
	v_readlane_b32 s60, v254, 44
	v_readlane_b32 s61, v254, 45
	v_readlane_b32 s62, v254, 46
	v_readlane_b32 s63, v254, 47
	s_waitcnt lgkmcnt(0)
	s_barrier
	s_branch .LBB0_702
